# baseline (speedup 1.0000x reference)
; #define LAS __attribute__((address_space(3)))
; __device__ __forceinline__ int obid() { int b = blockIdx.x; asm volatile("" : "+s"(b)); return b; }
; __device__ void attn_phase(LAS unsigned char* lds, const bf16_t* PROJ, bf16_t* AP, float* LSE) {
;     ...
;     int item = obid();
;     if (item < 4608) { const AttnItem a0 = attn_decode(item); ATTN_ISSUE(a0); }
;     if (tid < 256) { const int row = 256 + (tid >> 4), ch = tid & 15; unsigned z; asm volatile("v_mov_b32 %0, 0" : "=v"(z)); *(LAS u32x4*)(Vl + row * KP + ch * 16) = (u32x4){z, z, z, z}; }
;     for (; item < 4608; item += gridDim.x) {
;         const AttnItem a = attn_decode(item);
;         const int pat = a.pat, h = a.h, dsh = a.dsh, start = a.start, L = a.L, r = a.r, b = a.b;
.LBB0_305:
	v_mov_b32_e32 v204, 0x358637bd
	s_andn2_b64 vcc, exec, s[0:1]
	s_cbranch_vccnz .LBB0_371
	s_mov_b32 s101, 0
	v_mov_b32_e32 v70, v226
	s_mov_b32 s6, s66
	s_cmpk_lt_i32 s6, 0x1200
	s_cselect_b64 s[0:1], -1, 0
	s_cmpk_gt_i32 s6, 0x11ff
	v_readfirstlane_b32 s4, v70
	s_cbranch_scc1 .LBB0_329
	s_ashr_i32 s5, s6, 8
	s_cmp_lt_i32 s5, 6
	s_mov_b32 s2, 0
	s_cbranch_scc1 .LBB0_309
	s_lshr_b32 s2, s6, 8
	s_add_i32 s3, s2, 0xfffa
	s_and_b32 s2, s3, 0xff
	s_mulk_i32 s2, 0xab
	s_bfe_u32 s5, s2, 0x70009
	s_add_i32 s2, s5, 1
	s_mul_i32 s5, s5, 3
	s_sub_i32 s3, s3, s5
	s_and_b32 s2, s2, 0xff
	s_and_b32 s5, s3, 0xff

; #define LAS __attribute__((address_space(3)))
; __device__ void attn_phase(LAS unsigned char* lds, const bf16_t* PROJ, bf16_t* AP, float* LSE) {
;     ...
;         for (int it = 0; it < 8; ++it) { const int idx = tid + 512 * it, row = idx >> 4, ch = idx & 15; *(LAS u32x4*)(Kl + row * KP + ch * 16) = kreg[it]; *(LAS u32x4*)(Vl + row * KP + ch * 16) = vreg[it]; }
;         const int qi = 128 * b + 16 * wave + fr; const size_t qtok = (size_t)(start + r + (qi << dsh));
;         bf16x8 qf[4];
; #pragma unroll
;         for (int ks = 0; ks < 4; ++ks) qf[ks] = *(const bf16x8*)(PROJ + pj(qtok, h * 128 + 32 * ks + 8 * g));
;         __syncthreads();
;         if (item + (int)gridDim.x < 4608) { const AttnItem an = attn_decode(item + gridDim.x); ATTN_ISSUE(an); }
.LBB0_339:
	s_lshl_b32 s12, s16, 1
	s_lshr_b32 s4, s0, s12
	s_lshr_b32 s0, s4, 7
	s_ff1_i32_b32 s1, s0
	s_add_i32 s0, s0, -1
	s_and_b32 s0, s0, s3
	s_lshl_b32 s14, s0, 7
	s_add_i32 s14, s14, s7
	s_lshr_b32 s15, s3, s1
	v_or_b32_e32 v0, s14, v130
	s_add_i32 s15, s15, s2
	v_lshlrev_b32_e32 v0, s12, v0
	s_and_b32 s13, s6, 7
	v_add_u32_e32 v128, s15, v0
	v_ashrrev_i32_e32 v129, 31, v128
	s_mul_i32 s60, s13, 0x6000
	v_lshl_add_u64 v[2:3], v[128:129], 0, s[60:61]
	v_lshlrev_b64 v[2:3], 8, v[2:3]
	v_lshl_add_u64 v[2:3], v[118:119], 0, v[2:3]
	s_cmp_eq_u32 s101, 1
	s_cbranch_scc1 .Lattn_qmov
	global_load_dwordx4 v[80:83], v[2:3], off
	global_load_dwordx4 v[76:79], v[2:3], off offset:64
	global_load_dwordx4 v[72:75], v[2:3], off offset:128
	global_load_dwordx4 v[68:71], v[2:3], off offset:192
	s_branch .Lattn_qdone
.Lattn_qmov:
	s_waitcnt vmcnt(5)
	v_mov_b32_e32 v80, v236
	v_mov_b32_e32 v81, v237
	v_mov_b32_e32 v82, v238
	v_mov_b32_e32 v83, v239
	v_mov_b32_e32 v76, v240
	v_mov_b32_e32 v77, v241
	v_mov_b32_e32 v78, v242
	v_mov_b32_e32 v79, v243
	v_mov_b32_e32 v72, v244
	v_mov_b32_e32 v73, v245
	v_mov_b32_e32 v74, v246
	v_mov_b32_e32 v75, v247
	v_mov_b32_e32 v68, v248
	v_mov_b32_e32 v69, v249
	v_mov_b32_e32 v70, v250
	v_mov_b32_e32 v71, v251
.Lattn_qdone:
	v_add_u32_e32 v0, v131, v138
	s_waitcnt vmcnt(9)
	ds_write_b128 v0, v[8:11]
	v_add_u32_e32 v0, v132, v138
	ds_write_b128 v0, v[4:7]
	v_add_u32_e32 v0, v131, v140
	s_waitcnt vmcnt(7)
	ds_write_b128 v0, v[16:19]
	v_add_u32_e32 v0, v132, v140
	ds_write_b128 v0, v[12:15]
	v_add_u32_e32 v0, v131, v142
	s_waitcnt vmcnt(5)
	ds_write_b128 v0, v[24:27]
	v_add_u32_e32 v0, v132, v142
	ds_write_b128 v0, v[20:23]
	v_add_u32_e32 v0, v131, v144
	s_waitcnt vmcnt(4)
	ds_write_b128 v0, v[32:35]
	v_add_u32_e32 v0, v132, v144
	ds_write_b128 v0, v[28:31]
	v_add_u32_e32 v0, v131, v146
	ds_write_b128 v0, v[36:39]
	v_add_u32_e32 v0, v132, v146
	ds_write_b128 v0, v[40:43]
	v_add_u32_e32 v0, v131, v148
	ds_write_b128 v0, v[44:47]
	v_add_u32_e32 v0, v132, v148
	ds_write_b128 v0, v[48:51]
	v_add_u32_e32 v0, v131, v150
	s_add_i32 s6, s6, s10
	ds_write_b128 v0, v[52:55]
	v_add_u32_e32 v0, v132, v150
	s_cmpk_gt_i32 s6, 0x11ff
	ds_write_b128 v0, v[56:59]
	v_add_u32_e32 v0, v131, v152
	s_cselect_b64 s[0:1], -1, 0
	ds_write_b128 v0, v[60:63]
	v_add_u32_e32 v0, v132, v152
	s_and_b64 vcc, exec, s[0:1]
	ds_write_b128 v0, v[64:67]
	s_waitcnt lgkmcnt(0)
	s_barrier
	s_waitcnt vmcnt(0)
	s_cbranch_vccnz .LBB0_362
	s_ashr_i32 s5, s6, 8
	s_cmp_lt_i32 s5, 6
	s_mov_b32 s2, 0
	s_cbranch_scc1 .LBB0_342
	s_lshr_b32 s2, s6, 8
	s_add_i32 s3, s2, 0xfffa
	s_and_b32 s2, s3, 0xff
	s_mulk_i32 s2, 0xab
	s_bfe_u32 s5, s2, 0x70009
	s_add_i32 s2, s5, 1
	s_mul_i32 s5, s5, 3
	s_sub_i32 s3, s3, s5
	s_and_b32 s2, s2, 0xff
	s_and_b32 s5, s3, 0xff

; __device__ void attn_phase(LAS unsigned char* lds, const bf16_t* PROJ, bf16_t* AP, float* LSE) {
;     ...
;         const int qi = 128 * b + 16 * wave + fr; const size_t qtok = (size_t)(start + r + (qi << dsh));
;         bf16x8 qf[4];
; #pragma unroll
;         for (int ks = 0; ks < 4; ++ks) qf[ks] = *(const bf16x8*)(PROJ + pj(qtok, h * 128 + 32 * ks + 8 * g));
;         __syncthreads();
;         if (item + (int)gridDim.x < 4608) { const AttnItem an = attn_decode(item + gridDim.x); ATTN_ISSUE(an); }
.LBB0_361:
	s_or_b64 exec, exec, s[2:3]
	v_add_u32_e32 v232, s22, v130
	v_add_u32_e32 v232, s7, v232
	v_add_u32_e32 v232, 64, v232
	v_lshlrev_b32_e32 v232, s5, v232
	v_add_u32_e32 v232, s18, v232
	s_add_i32 s2, s20, 0xfffd0000
	v_add_u32_e32 v232, s2, v232
	v_mov_b32_e32 v233, v1
	v_lshlrev_b64 v[232:233], 8, v[232:233]
	v_lshl_add_u64 v[232:233], v[118:119], 0, v[232:233]
	global_load_dwordx4 v[236:239], v[232:233], off
	global_load_dwordx4 v[240:243], v[232:233], off offset:64
	global_load_dwordx4 v[244:247], v[232:233], off offset:128
	global_load_dwordx4 v[248:251], v[232:233], off offset:192
	s_mov_b32 s101, 1

; __global__ void __launch_bounds__(512, 2) fwd_megakernel(Params p) {
	.amdhsa_kernel _Z14fwd_megakernel6Params
		.amdhsa_group_segment_fixed_size 0
		.amdhsa_private_segment_fixed_size 0
		.amdhsa_kernarg_size 424
		.amdhsa_user_sgpr_count 2
		.amdhsa_user_sgpr_dispatch_ptr 0
		.amdhsa_user_sgpr_queue_ptr 0
		.amdhsa_user_sgpr_kernarg_segment_ptr 1
		.amdhsa_user_sgpr_dispatch_id 0
		.amdhsa_user_sgpr_kernarg_preload_length 0
		.amdhsa_user_sgpr_kernarg_preload_offset 0
		.amdhsa_user_sgpr_private_segment_size 0
		.amdhsa_uses_dynamic_stack 0
		.amdhsa_enable_private_segment 0
		.amdhsa_system_sgpr_workgroup_id_x 1
		.amdhsa_system_sgpr_workgroup_id_y 0
		.amdhsa_system_sgpr_workgroup_id_z 0
		.amdhsa_system_sgpr_workgroup_info 0
		.amdhsa_system_vgpr_workitem_id 2
		.amdhsa_next_free_vgpr 256
		.amdhsa_next_free_sgpr 102
		.amdhsa_accum_offset 256
		.amdhsa_reserve_vcc 1
		.amdhsa_float_round_mode_32 0
		.amdhsa_float_round_mode_16_64 0
		.amdhsa_float_denorm_mode_32 3
		.amdhsa_float_denorm_mode_16_64 3
		.amdhsa_dx10_clamp 1
		.amdhsa_ieee_mode 1
		.amdhsa_fp16_overflow 0
		.amdhsa_tg_split 0
		.amdhsa_exception_fp_ieee_invalid_op 0
		.amdhsa_exception_fp_denorm_src 0
		.amdhsa_exception_fp_ieee_div_zero 0
		.amdhsa_exception_fp_ieee_overflow 0
		.amdhsa_exception_fp_ieee_underflow 0
		.amdhsa_exception_fp_ieee_inexact 0
		.amdhsa_exception_int_div_zero 0
	.end_amdhsa_kernel

; __global__ void __launch_bounds__(512, 2) fwd_megakernel(Params p) {
amdhsa.kernels:
  - .agpr_count:     0
    .args:
      - .offset:         0
        .size:           168
        .value_kind:     by_value
      - .offset:         168
        .size:           4
        .value_kind:     hidden_block_count_x
      - .offset:         172
        .size:           4
        .value_kind:     hidden_block_count_y
      - .offset:         176
        .size:           4
        .value_kind:     hidden_block_count_z
      - .offset:         180
        .size:           2
        .value_kind:     hidden_group_size_x
      - .offset:         182
        .size:           2
        .value_kind:     hidden_group_size_y
      - .offset:         184
        .size:           2
        .value_kind:     hidden_group_size_z
      - .offset:         186
        .size:           2
        .value_kind:     hidden_remainder_x
      - .offset:         188
        .size:           2
        .value_kind:     hidden_remainder_y
      - .offset:         190
        .size:           2
        .value_kind:     hidden_remainder_z
      - .offset:         208
        .size:           8
        .value_kind:     hidden_global_offset_x
      - .offset:         216
        .size:           8
        .value_kind:     hidden_global_offset_y
      - .offset:         224
        .size:           8
        .value_kind:     hidden_global_offset_z
      - .offset:         232
        .size:           2
        .value_kind:     hidden_grid_dims
      - .offset:         256
        .size:           8
        .value_kind:     hidden_multigrid_sync_arg
      - .offset:         288
        .size:           4
        .value_kind:     hidden_dynamic_lds_size
    .group_segment_fixed_size: 0
    .kernarg_segment_align: 8
    .kernarg_segment_size: 424
    .language:       OpenCL C
    .language_version:
      - 2
      - 0
    .max_flat_workgroup_size: 512
    .name:           _Z14fwd_megakernel6Params
    .private_segment_fixed_size: 0
    .sgpr_count:     108
    .sgpr_spill_count: 190
    .symbol:         _Z14fwd_megakernel6Params.kd
    .uniform_work_group_size: 1
    .uses_dynamic_stack: false
    .vgpr_count:     256
    .vgpr_spill_count: 0
    .wavefront_size: 64
